# DPP/permlane wave sum also in the second (memory) rmsnorm pass of P0
# baseline (speedup 1.0000x reference)
; __device__ __forceinline__ void rms_pass(const float* X, const float* g, bf16_t* O, float* F, int rows, int gw, int NGW) {
;     ...
;     for (int m = gw; m < rows; m += 2 * NGW) {
;         const bool two = (m + NGW) < rows; const int m1 = two ? m + NGW : m;
;         const f32x4* x0 = (const f32x4*)(X + (size_t)m * 1024) + lane; const f32x4* x1 = (const f32x4*)(X + (size_t)m1 * 1024) + lane;
;         f32x4 v0[4], v1[4]; float s0 = 0.f, s1 = 0.f;
; #pragma unroll
;         for (int j = 0; j < 4; ++j) { v0[j] = x0[64 * j]; v1[j] = x1[64 * j]; }
; #pragma unroll
;         for (int j = 0; j < 4; ++j) { s0 += (v0[j].x * v0[j].x + v0[j].y * v0[j].y) + (v0[j].z * v0[j].z + v0[j].w * v0[j].w); s1 += (v1[j].x * v1[j].x + v1[j].y * v1[j].y) + (v1[j].z * v1[j].z + v1[j].w * v1[j].w); }
.LBB0_1334:
	s_add_i32 s30, s6, s77
	s_cmpk_lt_i32 s30, 0x800
	s_cselect_b64 s[14:15], -1, 0
	s_and_b64 s[8:9], s[14:15], exec
	s_cselect_b32 s8, s30, s6
	s_ashr_i32 s7, s6, 31
	s_lshl_b64 s[34:35], s[6:7], 12
	v_lshl_add_u64 v[6:7], v[38:39], 0, s[34:35]
	s_ashr_i32 s9, s8, 31
	global_load_dwordx4 v[26:29], v[6:7], off
	global_load_dwordx4 v[18:21], v[6:7], off offset:1024
	global_load_dwordx4 v[2:5], v[6:7], off offset:3072
	global_load_dwordx4 v[14:17], v[6:7], off offset:2048
	s_lshl_b64 s[34:35], s[8:9], 12
	v_lshl_add_u64 v[10:11], v[38:39], 0, s[34:35]
	global_load_dwordx4 v[30:33], v[10:11], off
	global_load_dwordx4 v[22:25], v[10:11], off offset:1024
	global_load_dwordx4 v[6:9], v[10:11], off offset:3072
	s_nop 0
	global_load_dwordx4 v[10:13], v[10:11], off offset:2048
	s_lshl_b64 s[34:35], s[6:7], 11
	s_lshl_b64 s[36:37], s[8:9], 11
	s_cmpk_gt_i32 s30, 0x7ff
	s_waitcnt vmcnt(7)
	v_pk_mul_f32 v[42:43], v[28:29], v[28:29]
	v_pk_mul_f32 v[44:45], v[26:27], v[26:27]
	s_waitcnt vmcnt(6)
	v_pk_mul_f32 v[46:47], v[20:21], v[20:21]
	v_pk_mul_f32 v[48:49], v[18:19], v[18:19]
	s_waitcnt vmcnt(4)
	v_mul_f32_e32 v58, v15, v15
	v_mul_f32_e32 v60, v17, v17
	v_pk_mov_b32 v[62:63], v[44:45], v[42:43] op_sel:[1,0]
	v_mov_b32_e32 v45, v43
	s_waitcnt vmcnt(3)
	v_pk_mul_f32 v[42:43], v[32:33], v[32:33]
	v_pk_mul_f32 v[64:65], v[30:31], v[30:31]
	v_pk_mov_b32 v[66:67], v[48:49], v[46:47] op_sel:[1,0]
	v_mov_b32_e32 v49, v47
	s_waitcnt vmcnt(2)
	v_pk_mul_f32 v[46:47], v[24:25], v[24:25]
	v_pk_mul_f32 v[68:69], v[22:23], v[22:23]
	v_mul_f32_e32 v73, v4, v4
	v_mul_f32_e32 v74, v5, v5
	v_pk_fma_f32 v[58:59], v[14:15], v[14:15], v[58:59] op_sel_hi:[1,1,0]
	v_pk_fma_f32 v[60:61], v[16:17], v[16:17], v[60:61] op_sel_hi:[1,1,0]
	v_pk_add_f32 v[44:45], v[62:63], v[44:45]
	v_pk_mov_b32 v[62:63], v[64:65], v[42:43] op_sel:[1,0]
	v_mov_b32_e32 v65, v43
	v_pk_add_f32 v[42:43], v[66:67], v[48:49]
	v_pk_mov_b32 v[48:49], v[68:69], v[46:47] op_sel:[1,0]
	v_mov_b32_e32 v69, v47
	v_mul_f32_e32 v57, v2, v2
	v_mul_f32_e32 v71, v3, v3
	v_mov_b32_e32 v59, v73
	v_mov_b32_e32 v61, v74
	v_pk_add_f32 v[62:63], v[62:63], v[64:65]
	v_pk_add_f32 v[48:49], v[48:49], v[68:69]
	v_pk_add_f32 v[44:45], v[44:45], v[44:45] op_sel:[0,1] op_sel_hi:[1,0]
	v_pk_add_f32 v[42:43], v[42:43], v[42:43] op_sel:[0,1] op_sel_hi:[1,0]
	s_waitcnt vmcnt(1)
	v_mul_f32_e32 v75, v6, v6
	v_mul_f32_e32 v76, v7, v7
	v_pk_add_f32 v[58:59], v[58:59], v[60:61]
	v_mov_b32_e32 v45, v57
	v_mov_b32_e32 v43, v71
	v_pk_add_f32 v[60:61], v[62:63], v[62:63] op_sel:[0,1] op_sel_hi:[1,0]
	v_pk_add_f32 v[48:49], v[48:49], v[48:49] op_sel:[0,1] op_sel_hi:[1,0]
	v_pk_add_f32 v[42:43], v[44:45], v[42:43]
	v_mov_b32_e32 v61, v75
	v_mov_b32_e32 v49, v76
	v_pk_add_f32 v[42:43], v[42:43], v[58:59]
	v_pk_add_f32 v[44:45], v[60:61], v[48:49]
	global_load_dwordx4 v[58:61], v[36:37], off
	s_waitcnt vmcnt(1)
; __device__ __forceinline__ unsigned cvt_pk_bf16(float lo, float hi) { unsigned r; asm volatile("v_cvt_pk_bf16_f32 %0, %1, %2" : "=v"(r) : "v"(lo), "v"(hi)); return r; }
; __device__ __forceinline__ float wave_sum(float v) {
; #pragma unroll
;     for (int o = 1; o < 64; o <<= 1) v += __shfl_xor(v, o);
;     return v;
; }
; __device__ __forceinline__ void rms_pass(const float* X, const float* g, bf16_t* O, float* F, int rows, int gw, int NGW) {
;     ...
;         for (int j = 0; j < 4; ++j) { s0 += (v0[j].x * v0[j].x + v0[j].y * v0[j].y) + (v0[j].z * v0[j].z + v0[j].w * v0[j].w); s1 += (v1[j].x * v1[j].x + v1[j].y * v1[j].y) + (v1[j].z * v1[j].z + v1[j].w * v1[j].w); }
;         const float r0 = 1.0f / sqrtf(wave_sum(s0) * (1.f / 1024.f) + 1e-6f), r1 = 1.0f / sqrtf(wave_sum(s1) * (1.f / 1024.f) + 1e-6f);
; #pragma unroll
;         for (int j = 0; j < 4; ++j) {
;             const f32x4 gg = gr[64 * j]; const f32x4 y0 = v0[j] * r0 * gg, y1 = v1[j] * r1 * gg;
;             u32x2 w0, w1; w0.x = cvt_pk_bf16(y0.x, y0.y); w0.y = cvt_pk_bf16(y0.z, y0.w); w1.x = cvt_pk_bf16(y1.x, y1.y); w1.y = cvt_pk_bf16(y1.z, y1.w);
;             *((u32x2*)(O + (size_t)m * 1024) + lane + 64 * j) = w0;
;             if (two) *((u32x2*)(O + (size_t)m1 * 1024) + lane + 64 * j) = w1;
;         }
	v_mul_f32_e32 v70, v11, v11
	v_mul_f32_e32 v72, v13, v13
	v_mul_f32_e32 v77, v8, v8
	v_mul_f32_e32 v78, v9, v9
	v_pk_fma_f32 v[46:47], v[10:11], v[10:11], v[70:71] op_sel_hi:[1,1,0]
	v_pk_fma_f32 v[66:67], v[12:13], v[12:13], v[72:73] op_sel_hi:[1,1,0]
	v_mov_b32_e32 v47, v77
	v_mov_b32_e32 v67, v78
	v_pk_add_f32 v[46:47], v[46:47], v[66:67]
	v_add_f32_e32 v48, v42, v43
	v_pk_add_f32 v[42:43], v[44:45], v[46:47]
	v_add_f32_e32 v42, v42, v43
	v_mov_b32_e32 v44, v48
	s_nop 1
	v_add_f32_dpp v44, v44, v44 quad_perm:[1,0,3,2] row_mask:0xf bank_mask:0xf
	v_add_f32_dpp v42, v42, v42 quad_perm:[1,0,3,2] row_mask:0xf bank_mask:0xf
	s_nop 0
	v_add_f32_dpp v44, v44, v44 quad_perm:[2,3,0,1] row_mask:0xf bank_mask:0xf
	v_add_f32_dpp v42, v42, v42 quad_perm:[2,3,0,1] row_mask:0xf bank_mask:0xf
	s_nop 0
	v_add_f32_dpp v44, v44, v44 row_half_mirror row_mask:0xf bank_mask:0xf
	v_add_f32_dpp v42, v42, v42 row_half_mirror row_mask:0xf bank_mask:0xf
	s_nop 0
	v_add_f32_dpp v44, v44, v44 row_mirror row_mask:0xf bank_mask:0xf
	v_add_f32_dpp v42, v42, v42 row_mirror row_mask:0xf bank_mask:0xf
	s_nop 0
	v_mov_b32_e32 v45, v44
	v_mov_b32_e32 v43, v42
	s_nop 1
	v_permlane16_swap_b32_e32 v44, v45
	v_permlane16_swap_b32_e32 v42, v43
	s_nop 1
	v_add_f32_e32 v44, v44, v45
	v_add_f32_e32 v42, v42, v43
	v_mov_b32_e32 v45, v44
	v_mov_b32_e32 v43, v42
	s_nop 1
	v_permlane32_swap_b32_e32 v44, v45
	v_permlane32_swap_b32_e32 v42, v43
	s_nop 1
	v_add_f32_e32 v44, v44, v45
	v_add_f32_e32 v42, v42, v43
	v_fmamk_f32 v44, v44, 0x3a800000, v55
	v_mul_f32_e32 v43, 0x4f800000, v44
	v_cmp_gt_f32_e32 vcc, s13, v44
	v_fmamk_f32 v42, v42, 0x3a800000, v55
	v_cmp_gt_f32_e64 s[6:7], s13, v42
	v_cndmask_b32_e32 v43, v44, v43, vcc
	v_mul_f32_e32 v44, 0x4f800000, v42
	v_sqrt_f32_e32 v45, v43
	v_cndmask_b32_e64 v42, v42, v44, s[6:7]
	v_sqrt_f32_e32 v44, v42
	v_add_u32_e32 v46, -1, v45
	v_add_u32_e32 v47, 1, v45
	v_fma_f32 v48, -v46, v45, v43
	v_fma_f32 v49, -v47, v45, v43
	v_add_u32_e32 v57, -1, v44
	v_cmp_ge_f32_e64 s[8:9], 0, v48
	v_add_u32_e32 v62, 1, v44
	v_fma_f32 v48, -v62, v44, v42
	v_cndmask_b32_e64 v45, v45, v46, s[8:9]
	v_fma_f32 v46, -v57, v44, v42
	v_cmp_lt_f32_e64 s[8:9], 0, v49
	s_nop 1
	v_cndmask_b32_e64 v45, v45, v47, s[8:9]
	v_cmp_ge_f32_e64 s[8:9], 0, v46
	v_mul_f32_e32 v46, 0x37800000, v45
	v_cndmask_b32_e32 v45, v45, v46, vcc
	v_cndmask_b32_e64 v44, v44, v57, s[8:9]
	v_cmp_lt_f32_e64 s[8:9], 0, v48
	v_cmp_class_f32_e32 vcc, v43, v56
	s_nop 0
	v_cndmask_b32_e64 v44, v44, v62, s[8:9]
	v_mul_f32_e32 v46, 0x37800000, v44
	v_cndmask_b32_e32 v43, v45, v43, vcc
	v_cndmask_b32_e64 v44, v44, v46, s[6:7]
	v_div_scale_f32 v45, s[6:7], v43, v43, 1.0
	v_cmp_class_f32_e64 s[6:7], v42, v56
	v_div_scale_f32 v46, vcc, 1.0, v43, 1.0
	s_nop 0
	v_cndmask_b32_e64 v42, v44, v42, s[6:7]
	v_rcp_f32_e32 v44, v45
	v_div_scale_f32 v47, s[6:7], v42, v42, 1.0
	v_rcp_f32_e32 v49, v47
	v_fma_f32 v48, -v45, v44, 1.0
	v_fmac_f32_e32 v44, v48, v44
	v_mul_f32_e32 v62, v46, v44
	v_fma_f32 v48, -v47, v49, 1.0
	v_fmac_f32_e32 v49, v48, v49
	v_fma_f32 v48, -v45, v62, v46
	v_fmac_f32_e32 v62, v48, v44
	v_fma_f32 v45, -v45, v62, v46
	v_div_scale_f32 v57, s[6:7], 1.0, v42, 1.0
	v_div_fmas_f32 v44, v45, v44, v62
	v_div_fixup_f32 v48, v44, v43, 1.0
	v_mul_f32_e32 v43, v57, v49
	v_fma_f32 v44, -v47, v43, v57
	v_fmac_f32_e32 v43, v44, v49
	v_fma_f32 v44, -v47, v43, v57
	s_mov_b64 vcc, s[6:7]
	v_div_fmas_f32 v43, v44, v49, v43
	v_div_fixup_f32 v46, v43, v42, 1.0
	v_pk_mul_f32 v[26:27], v[26:27], v[48:49] op_sel_hi:[1,0]
	v_lshl_add_u64 v[44:45], v[40:41], 0, s[34:35]
	v_lshl_add_u64 v[42:43], v[40:41], 0, s[36:37]
	v_pk_mul_f32 v[28:29], v[28:29], v[48:49] op_sel_hi:[1,0]
	s_waitcnt vmcnt(0)
	v_pk_mul_f32 v[26:27], v[58:59], v[26:27]
	v_pk_mul_f32 v[30:31], v[30:31], v[46:47] op_sel_hi:[1,0]
	v_pk_mul_f32 v[32:33], v[32:33], v[46:47] op_sel_hi:[1,0]
	v_pk_mul_f32 v[28:29], v[60:61], v[28:29]
	v_pk_mul_f32 v[32:33], v[60:61], v[32:33]
	v_pk_mul_f32 v[30:31], v[58:59], v[30:31]
	v_cvt_pk_bf16_f32 v58, v26, v27
	v_cvt_pk_bf16_f32 v59, v28, v29
	s_nop 0
	v_cvt_pk_bf16_f32 v26, v30, v31
	v_cvt_pk_bf16_f32 v27, v32, v33
	global_store_dwordx2 v[44:45], v[58:59], off
	s_cbranch_scc1 .LBB0_1336
	global_store_dwordx2 v[42:43], v[26:27], off
